# layer-1 W_in transposes moved into the layer-0 out-projection tile loop (half the XCDs before each tile, default-policy stores); W_out transposes stay in mixer pass 1
# baseline (speedup 1.0000x reference)
.Ldt0_nrot:
	s_addk_i32 s52, 0xa08
	s_mul_i32 s9, s84, 10
	s_add_u32 s52, s52, s9
	s_movk_i32 s9, 0x1c10
	s_cmp_ge_u32 s52, s9
	s_cbranch_scc1 .Ldt0_skip
	s_waitcnt lgkmcnt(0)
	s_barrier
	v_readlane_b32 s54, v254, 54
	v_readlane_b32 s55, v254, 55
	v_readlane_b32 s56, v253, 2
	v_readlane_b32 s57, v253, 3
	v_readlane_b32 s58, v253, 8
	v_readlane_b32 s59, v253, 9
	v_readlane_b32 s60, v253, 10
	v_readlane_b32 s61, v253, 11
	v_readlane_b32 s62, v254, 12
	v_readlane_b32 s63, v254, 13
	v_and_b32_e32 v106, 7, v180
	v_lshrrev_b32_e32 v93, 3, v180
	s_add_u32 s54, s54, 0xa080000
	s_addc_u32 s55, s55, 0
	s_add_u32 s58, s58, 0x5000000
	s_addc_u32 s59, s59, 0
	s_add_u32 s60, s60, 0x40000
	s_addc_u32 s61, s61, 0
	v_lshlrev_b32_e32 v94, 4, v106
	v_bfe_u32 v107, v180, 3, 1
	v_lshlrev_b32_e32 v108, 2, v106
	v_lshl_add_u32 v108, v107, 1, v108
	v_mul_u32_u24_e32 v84, 0x410, v108
	v_lshrrev_b32_e32 v109, 3, v93
	v_xor_b32_e32 v109, v109, v106
	v_lshlrev_b32_e32 v109, 3, v109
	v_and_b32_e32 v110, 6, v93
	v_or_b32_e32 v109, v109, v110
	v_lshl_add_u32 v84, v109, 1, v84
	v_cmp_ne_u32_e64 s[74:75], 0, v107
	v_mov_b32_e32 v104, 0x1000504
	v_mov_b32_e32 v105, 0x3020706
	v_mov_b32_e32 v111, 0x5040100
	v_mov_b32_e32 v112, 0x7060302
	v_cndmask_b32_e64 v104, v104, v111, s[74:75]
	v_cndmask_b32_e64 v105, v105, v112, s[74:75]
	v_lshrrev_b32_e32 v106, 6, v180
	v_and_b32_e32 v107, 63, v180
	v_lshrrev_b32_e32 v108, 2, v106
	v_add_u32_e32 v109, 0, v108
	v_xor_b32_e32 v109, v109, v107
	v_lshlrev_b32_e32 v109, 4, v109
	v_add_u32_e32 v110, 0, v106
	v_mul_u32_u24_e32 v110, 0x410, v110
	v_add_u32_e32 v85, v109, v110
	v_add_u32_e32 v109, 2, v108
	v_xor_b32_e32 v109, v109, v107
	v_lshlrev_b32_e32 v109, 4, v109
	v_add_u32_e32 v110, 8, v106
	v_mul_u32_u24_e32 v110, 0x410, v110
	v_add_u32_e32 v86, v109, v110
	v_add_u32_e32 v109, 4, v108
	v_xor_b32_e32 v109, v109, v107
	v_lshlrev_b32_e32 v109, 4, v109
	v_add_u32_e32 v110, 16, v106
	v_mul_u32_u24_e32 v110, 0x410, v110
	v_add_u32_e32 v87, v109, v110
	v_add_u32_e32 v109, 6, v108
	v_xor_b32_e32 v109, v109, v107
	v_lshlrev_b32_e32 v109, 4, v109
	v_add_u32_e32 v110, 24, v106
	v_mul_u32_u24_e32 v110, 0x410, v110
	v_add_u32_e32 v88, v109, v110
	v_lshlrev_b32_e32 v109, 13, v106
	v_lshl_add_u32 v89, v107, 4, v109
	v_add_u32_e32 v90, 0x10000, v89
	v_add_u32_e32 v91, 0x20000, v89
	v_add_u32_e32 v92, 0x30000, v89
	s_mov_b32 s53, 0
	s_mov_b32 s73, 0
	s_cmpk_ge_u32 s52, 0x1410
	s_cbranch_scc1 .Ldt0_out0
	s_sub_i32 s0, s52, 0xa08
	s_mul_i32 s1, s0, 0xcc3
	s_lshr_b32 s1, s1, 20
	s_mul_i32 s2, s1, 0x141
	s_sub_u32 s2, s0, s2
	s_lshl_b32 s3, s2, 7
	s_mul_i32 s4, s1, 0x1410000
	s_add_u32 s3, s3, s4
	s_add_u32 s64, s54, s3
	s_addc_u32 s65, s55, 0
	s_mov_b32 s7, 0xa080
	s_lshl_b32 s4, s1, 10
	s_cmpk_lt_u32 s2, 0x80
	s_cbranch_scc1 .Ldt0_wlo0
	s_cmpk_eq_u32 s2, 0x80
	s_cbranch_scc1 .Ldt0_wlr0
	s_add_i32 s2, s2, -1

.LBB0_805:
	s_sub_u32 s0, s56, s96
	s_bfe_u32 s2, s96, 0x10002
	s_mul_i32 s2, s2, s94
	s_cmp_lg_u32 s0, s2
	s_cbranch_scc1 .Ldt3_skip
	s_mov_b32 s57, s96
	s_cmpk_lg_u32 s94, 0x100
	s_cbranch_scc1 .Ldt3_nrot
	s_xor_b32 s57, s57, 0x80
.Ldt3_nrot:
	s_addk_i32 s57, 0xa08
	s_mul_i32 s32, s94, 10
	s_addk_i32 s32, 0xa08
	s_min_u32 s32, s32, 0x1c10
	s_cmp_ge_u32 s57, s32
	s_cbranch_scc1 .Ldt3_skip
	s_waitcnt lgkmcnt(0)
	s_barrier
	v_readlane_b32 s60, v254, 54
	v_readlane_b32 s61, v254, 55
	v_readlane_b32 s62, v253, 2
	v_readlane_b32 s63, v253, 3
	v_readlane_b32 s64, v253, 8
	v_readlane_b32 s65, v253, 9
	v_readlane_b32 s66, v253, 10
	v_readlane_b32 s67, v253, 11
	v_readlane_b32 s68, v254, 12
	v_readlane_b32 s69, v254, 13
	v_and_b32_e32 v106, 7, v180
	v_lshrrev_b32_e32 v93, 3, v180
	s_add_u32 s60, s60, 0xa080000
	s_addc_u32 s61, s61, 0
	s_add_u32 s64, s64, 0x5000000
	s_addc_u32 s65, s65, 0
	s_add_u32 s66, s66, 0x40000
	s_addc_u32 s67, s67, 0
	v_lshlrev_b32_e32 v94, 4, v106
	v_bfe_u32 v107, v180, 3, 1
	v_lshlrev_b32_e32 v108, 2, v106
	v_lshl_add_u32 v108, v107, 1, v108
	v_mul_u32_u24_e32 v84, 0x410, v108
	v_lshrrev_b32_e32 v109, 3, v93
	v_xor_b32_e32 v109, v109, v106
	v_lshlrev_b32_e32 v109, 3, v109
	v_and_b32_e32 v110, 6, v93
	v_or_b32_e32 v109, v109, v110
	v_lshl_add_u32 v84, v109, 1, v84
	v_cmp_ne_u32_e64 s[80:81], 0, v107
	v_mov_b32_e32 v104, 0x1000504
	v_mov_b32_e32 v105, 0x3020706
	v_mov_b32_e32 v111, 0x5040100
	v_mov_b32_e32 v112, 0x7060302
	v_cndmask_b32_e64 v104, v104, v111, s[80:81]
	v_cndmask_b32_e64 v105, v105, v112, s[80:81]
	v_lshrrev_b32_e32 v106, 6, v180
	v_and_b32_e32 v107, 63, v180
	v_lshrrev_b32_e32 v108, 2, v106
	v_add_u32_e32 v109, 0, v108
	v_xor_b32_e32 v109, v109, v107
	v_lshlrev_b32_e32 v109, 4, v109
	v_add_u32_e32 v110, 0, v106
	v_mul_u32_u24_e32 v110, 0x410, v110
	v_add_u32_e32 v85, v109, v110
	v_add_u32_e32 v109, 2, v108
	v_xor_b32_e32 v109, v109, v107
	v_lshlrev_b32_e32 v109, 4, v109
	v_add_u32_e32 v110, 8, v106
	v_mul_u32_u24_e32 v110, 0x410, v110
	v_add_u32_e32 v86, v109, v110
	v_add_u32_e32 v109, 4, v108
	v_xor_b32_e32 v109, v109, v107
	v_lshlrev_b32_e32 v109, 4, v109
	v_add_u32_e32 v110, 16, v106
	v_mul_u32_u24_e32 v110, 0x410, v110
	v_add_u32_e32 v87, v109, v110
	v_add_u32_e32 v109, 6, v108
	v_xor_b32_e32 v109, v109, v107
	v_lshlrev_b32_e32 v109, 4, v109
	v_add_u32_e32 v110, 24, v106
	v_mul_u32_u24_e32 v110, 0x410, v110
	v_add_u32_e32 v88, v109, v110
	v_lshlrev_b32_e32 v109, 13, v106
	v_lshl_add_u32 v89, v107, 4, v109
	v_add_u32_e32 v90, 0x10000, v89
	v_add_u32_e32 v91, 0x20000, v89
	v_add_u32_e32 v92, 0x30000, v89
	s_mov_b32 s58, 0
	s_mov_b32 s79, 0
	s_cmpk_ge_u32 s57, 0x1410
	s_cbranch_scc1 .Ldt3_out0
	s_sub_i32 s0, s57, 0xa08
	s_mul_i32 s2, s0, 0xcc3
	s_lshr_b32 s2, s2, 20
	s_mul_i32 s3, s2, 0x141
	s_sub_u32 s3, s0, s3
	s_lshl_b32 s17, s3, 7
	s_mul_i32 s20, s2, 0x1410000
	s_add_u32 s17, s17, s20
	s_add_u32 s70, s60, s17
	s_addc_u32 s71, s61, 0
	s_mov_b32 s25, 0xa080
	s_lshl_b32 s20, s2, 10
	s_cmpk_lt_u32 s3, 0x80
	s_cbranch_scc1 .Ldt3_wlo0
	s_cmpk_eq_u32 s3, 0x80
	s_cbranch_scc1 .Ldt3_wlr0
	s_add_i32 s3, s3, -1
.Ldt3_wlo0:
	s_lshl_b32 s21, s3, 18
	s_add_u32 s21, s21, s20
	s_add_u32 s72, s64, s21
	s_addc_u32 s73, s65, 0
	s_branch .Ldt3_ud0
.Ldt3_wlr0:
	s_add_u32 s72, s66, s20
	s_addc_u32 s73, s67, 0
	s_branch .Ldt3_ud0
.Ldt3_out0:
	s_sub_i32 s0, s57, 0x1410
	s_lshr_b32 s2, s0, 10
	s_bfe_u32 s3, s0, 0x30007
	s_and_b32 s17, s0, 0x7f
	s_lshl_b32 s20, s2, 26
	s_lshl_b32 s21, s17, 7
	s_add_u32 s20, s20, s21
	s_lshl_b32 s21, s3, 23
	s_add_u32 s20, s20, s21
	s_add_u32 s70, s62, s20
	s_addc_u32 s71, s63, 0
	s_lshl_b32 s20, s2, 25
	s_lshl_b32 s21, s17, 18
	s_add_u32 s20, s20, s21
	s_lshl_b32 s21, s3, 10
	s_add_u32 s20, s20, s21
	s_add_u32 s72, s68, s20
	s_addc_u32 s73, s69, 0
	s_movk_i32 s25, 0x4000
.Ldt3_ud0:
	v_mul_u32_u24_e32 v96, s25, v93
	s_lshl_b32 s24, s25, 6
	v_add_u32_e32 v96, v96, v94
	v_add_u32_e32 v97, s24, v96
	v_add_u32_e32 v98, s24, v97
	v_add_u32_e32 v99, s24, v98
	v_add_u32_e32 v100, s24, v99
	v_add_u32_e32 v101, s24, v100
	v_add_u32_e32 v102, s24, v101
	v_add_u32_e32 v103, s24, v102
	global_load_dwordx4 v[4:7], v96, s[70:71] nt
	global_load_dwordx4 v[8:11], v97, s[70:71] nt
	global_load_dwordx4 v[12:15], v98, s[70:71] nt
	global_load_dwordx4 v[16:19], v99, s[70:71] nt
	global_load_dwordx4 v[20:23], v100, s[70:71] nt
	global_load_dwordx4 v[24:27], v101, s[70:71] nt
	global_load_dwordx4 v[28:31], v102, s[70:71] nt
	global_load_dwordx4 v[32:35], v103, s[70:71] nt
	s_mov_b32 s78, 1
	s_add_u32 s57, s57, s94
	s_cmp_ge_u32 s57, s32
	s_cbranch_scc1 .Ldt3_procA
	s_cmpk_ge_u32 s57, 0x1410
	s_cbranch_scc1 .Ldt3_out1
	s_sub_i32 s0, s57, 0xa08
	s_mul_i32 s2, s0, 0xcc3
	s_lshr_b32 s2, s2, 20
	s_mul_i32 s3, s2, 0x141
	s_sub_u32 s3, s0, s3
	s_lshl_b32 s17, s3, 7
	s_mul_i32 s20, s2, 0x1410000
	s_add_u32 s17, s17, s20
	s_add_u32 s74, s60, s17
	s_addc_u32 s75, s61, 0
	s_mov_b32 s25, 0xa080
	s_lshl_b32 s20, s2, 10
	s_cmpk_lt_u32 s3, 0x80
	s_cbranch_scc1 .Ldt3_wlo1
	s_cmpk_eq_u32 s3, 0x80
	s_cbranch_scc1 .Ldt3_wlr1
	s_add_i32 s3, s3, -1
.Ldt3_wlo1:
	s_lshl_b32 s21, s3, 18
	s_add_u32 s21, s21, s20
	s_add_u32 s34, s64, s21
	s_addc_u32 s35, s65, 0
	s_branch .Ldt3_ud1
.Ldt3_wlr1:
	s_add_u32 s34, s66, s20
	s_addc_u32 s35, s67, 0
	s_branch .Ldt3_ud1
.Ldt3_out1:
	s_sub_i32 s0, s57, 0x1410
	s_lshr_b32 s2, s0, 10
	s_bfe_u32 s3, s0, 0x30007
	s_and_b32 s17, s0, 0x7f
	s_lshl_b32 s20, s2, 26
	s_lshl_b32 s21, s17, 7
	s_add_u32 s20, s20, s21
	s_lshl_b32 s21, s3, 23
	s_add_u32 s20, s20, s21
	s_add_u32 s74, s62, s20
	s_addc_u32 s75, s63, 0
	s_lshl_b32 s20, s2, 25
	s_lshl_b32 s21, s17, 18
	s_add_u32 s20, s20, s21
	s_lshl_b32 s21, s3, 10
	s_add_u32 s20, s20, s21
	s_add_u32 s34, s68, s20
	s_addc_u32 s35, s69, 0
	s_movk_i32 s25, 0x4000
.Ldt3_ud1:
	v_mul_u32_u24_e32 v96, s25, v93
	s_lshl_b32 s24, s25, 6
	v_add_u32_e32 v96, v96, v94
	v_add_u32_e32 v97, s24, v96
	v_add_u32_e32 v98, s24, v97
	v_add_u32_e32 v99, s24, v98
	v_add_u32_e32 v100, s24, v99
	v_add_u32_e32 v101, s24, v100
	v_add_u32_e32 v102, s24, v101
	v_add_u32_e32 v103, s24, v102
	global_load_dwordx4 v[36:39], v96, s[74:75] nt
	global_load_dwordx4 v[40:43], v97, s[74:75] nt
	global_load_dwordx4 v[44:47], v98, s[74:75] nt
	global_load_dwordx4 v[48:51], v99, s[74:75] nt
	global_load_dwordx4 v[52:55], v100, s[74:75] nt
	global_load_dwordx4 v[56:59], v101, s[74:75] nt
	global_load_dwordx4 v[60:63], v102, s[74:75] nt
	global_load_dwordx4 v[64:67], v103, s[74:75] nt
	s_mov_b32 s79, 1
	s_add_u32 s57, s57, s94
.Ldt3_procA:
	s_cmp_eq_u32 s79, 0
	s_cbranch_scc1 .Ldt3_w0A
	s_cmp_lt_u32 s58, 2
	s_cbranch_scc1 .Ldt3_wsA
	s_waitcnt vmcnt(16)
	s_branch .Ldt3_wdA
.Ldt3_wsA:
	s_cmp_eq_u32 s58, 0
	s_cbranch_scc1 .Ldt3_w8A
	s_waitcnt vmcnt(12)
	s_branch .Ldt3_wdA

.Ldt3_wdA:
	v_cvt_pk_bf16_f32 v4, v4, v5
	v_cvt_pk_bf16_f32 v6, v6, v7
	v_cvt_pk_bf16_f32 v8, v8, v9
	v_cvt_pk_bf16_f32 v10, v10, v11
	v_cvt_pk_bf16_f32 v12, v12, v13
	v_cvt_pk_bf16_f32 v14, v14, v15
	v_cvt_pk_bf16_f32 v16, v16, v17
	v_cvt_pk_bf16_f32 v18, v18, v19
	v_cvt_pk_bf16_f32 v20, v20, v21
	v_cvt_pk_bf16_f32 v22, v22, v23
	v_cvt_pk_bf16_f32 v24, v24, v25
	v_cvt_pk_bf16_f32 v26, v26, v27
	v_cvt_pk_bf16_f32 v28, v28, v29
	v_cvt_pk_bf16_f32 v30, v30, v31
	v_cvt_pk_bf16_f32 v32, v32, v33
	v_cvt_pk_bf16_f32 v34, v34, v35
	v_cndmask_b32_e64 v5, v6, v4, s[80:81]
	v_cndmask_b32_e64 v7, v4, v6, s[80:81]
	v_cndmask_b32_e64 v9, v10, v8, s[80:81]
	v_cndmask_b32_e64 v11, v8, v10, s[80:81]
	v_cndmask_b32_e64 v13, v14, v12, s[80:81]
	v_cndmask_b32_e64 v15, v12, v14, s[80:81]
	v_cndmask_b32_e64 v17, v18, v16, s[80:81]
	v_cndmask_b32_e64 v19, v16, v18, s[80:81]
	v_cndmask_b32_e64 v21, v22, v20, s[80:81]
	v_cndmask_b32_e64 v23, v20, v22, s[80:81]
	v_cndmask_b32_e64 v25, v26, v24, s[80:81]
	v_cndmask_b32_e64 v27, v24, v26, s[80:81]
	v_cndmask_b32_e64 v29, v30, v28, s[80:81]
	v_cndmask_b32_e64 v31, v28, v30, s[80:81]
	v_cndmask_b32_e64 v33, v34, v32, s[80:81]
	v_cndmask_b32_e64 v35, v32, v34, s[80:81]
	v_mov_b32_dpp v4, v5 row_ror:8 row_mask:0xf bank_mask:0xf
	v_mov_b32_dpp v8, v9 row_ror:8 row_mask:0xf bank_mask:0xf
	v_mov_b32_dpp v12, v13 row_ror:8 row_mask:0xf bank_mask:0xf
	v_mov_b32_dpp v16, v17 row_ror:8 row_mask:0xf bank_mask:0xf
	v_mov_b32_dpp v20, v21 row_ror:8 row_mask:0xf bank_mask:0xf
	v_mov_b32_dpp v24, v25 row_ror:8 row_mask:0xf bank_mask:0xf
	v_mov_b32_dpp v28, v29 row_ror:8 row_mask:0xf bank_mask:0xf
	v_mov_b32_dpp v32, v33 row_ror:8 row_mask:0xf bank_mask:0xf
	s_nop 1
	v_perm_b32 v68, v7, v4, v104
	v_perm_b32 v69, v7, v4, v105
	v_perm_b32 v70, v11, v8, v104
	v_perm_b32 v71, v11, v8, v105
	v_perm_b32 v72, v15, v12, v104
	v_perm_b32 v73, v15, v12, v105
	v_perm_b32 v74, v19, v16, v104
	v_perm_b32 v75, v19, v16, v105
	v_perm_b32 v76, v23, v20, v104
	v_perm_b32 v77, v23, v20, v105
	v_perm_b32 v78, v27, v24, v104
	v_perm_b32 v79, v27, v24, v105
	v_perm_b32 v80, v31, v28, v104
	v_perm_b32 v81, v31, v28, v105
	v_perm_b32 v82, v35, v32, v104
	v_perm_b32 v83, v35, v32, v105
	s_mov_b64 s[76:77], s[72:73]
	s_mov_b32 s78, 0
	s_cmp_ge_u32 s57, s32
	s_cbranch_scc1 .Ldt3_nlA
	s_cmpk_ge_u32 s57, 0x1410
	s_cbranch_scc1 .Ldt3_out2
	s_sub_i32 s0, s57, 0xa08
	s_mul_i32 s2, s0, 0xcc3
	s_lshr_b32 s2, s2, 20
	s_mul_i32 s3, s2, 0x141
	s_sub_u32 s3, s0, s3
	s_lshl_b32 s17, s3, 7
	s_mul_i32 s20, s2, 0x1410000
	s_add_u32 s17, s17, s20
	s_add_u32 s70, s60, s17
	s_addc_u32 s71, s61, 0
	s_mov_b32 s25, 0xa080
	s_lshl_b32 s20, s2, 10
	s_cmpk_lt_u32 s3, 0x80
	s_cbranch_scc1 .Ldt3_wlo2
	s_cmpk_eq_u32 s3, 0x80
	s_cbranch_scc1 .Ldt3_wlr2
	s_add_i32 s3, s3, -1

.Ldt3_ud2:
	v_mul_u32_u24_e32 v96, s25, v93
	s_lshl_b32 s24, s25, 6
	v_add_u32_e32 v96, v96, v94
	v_add_u32_e32 v97, s24, v96
	v_add_u32_e32 v98, s24, v97
	v_add_u32_e32 v99, s24, v98
	v_add_u32_e32 v100, s24, v99
	v_add_u32_e32 v101, s24, v100
	v_add_u32_e32 v102, s24, v101
	v_add_u32_e32 v103, s24, v102
	global_load_dwordx4 v[4:7], v96, s[70:71] nt
	global_load_dwordx4 v[8:11], v97, s[70:71] nt
	global_load_dwordx4 v[12:15], v98, s[70:71] nt
	global_load_dwordx4 v[16:19], v99, s[70:71] nt
	global_load_dwordx4 v[20:23], v100, s[70:71] nt
	global_load_dwordx4 v[24:27], v101, s[70:71] nt
	global_load_dwordx4 v[28:31], v102, s[70:71] nt
	global_load_dwordx4 v[32:35], v103, s[70:71] nt
	s_mov_b32 s78, 1
	s_add_u32 s57, s57, s94
.Ldt3_nlA:
	ds_write_b32 v84, v68 offset:0
	ds_write_b32 v84, v69 offset:1040
	ds_write_b32 v84, v70 offset:128
	ds_write_b32 v84, v71 offset:1168
	ds_write_b32 v84, v72 offset:256
	ds_write_b32 v84, v73 offset:1296
	ds_write_b32 v84, v74 offset:384
	ds_write_b32 v84, v75 offset:1424
	ds_write_b32 v84, v76 offset:512
	ds_write_b32 v84, v77 offset:1552
	ds_write_b32 v84, v78 offset:640
	ds_write_b32 v84, v79 offset:1680
	ds_write_b32 v84, v80 offset:768
	ds_write_b32 v84, v81 offset:1808
	ds_write_b32 v84, v82 offset:896
	ds_write_b32 v84, v83 offset:1936
	s_waitcnt lgkmcnt(0)
	s_barrier
	ds_read_b128 v[68:71], v85 offset:0
	ds_read_b128 v[72:75], v86 offset:0
	ds_read_b128 v[76:79], v87 offset:0
	ds_read_b128 v[80:83], v88 offset:0
	s_waitcnt lgkmcnt(3)
	global_store_dwordx4 v89, v[68:71], s[76:77]
	s_waitcnt lgkmcnt(2)
	global_store_dwordx4 v90, v[72:75], s[76:77]
	s_waitcnt lgkmcnt(1)
	global_store_dwordx4 v91, v[76:79], s[76:77]
	s_waitcnt lgkmcnt(0)
	global_store_dwordx4 v92, v[80:83], s[76:77]
	s_add_u32 s58, s58, 1
	s_cmp_eq_u32 s79, 0
	s_cbranch_scc1 .Ldt3_end
.Ldt3_procB:
	s_cmp_eq_u32 s78, 0
	s_cbranch_scc1 .Ldt3_w0B
	s_cmp_lt_u32 s58, 2
	s_cbranch_scc1 .Ldt3_wsB
	s_waitcnt vmcnt(16)
	s_branch .Ldt3_wdB

.Ldt3_wdB:
	v_cvt_pk_bf16_f32 v36, v36, v37
	v_cvt_pk_bf16_f32 v38, v38, v39
	v_cvt_pk_bf16_f32 v40, v40, v41
	v_cvt_pk_bf16_f32 v42, v42, v43
	v_cvt_pk_bf16_f32 v44, v44, v45
	v_cvt_pk_bf16_f32 v46, v46, v47
	v_cvt_pk_bf16_f32 v48, v48, v49
	v_cvt_pk_bf16_f32 v50, v50, v51
	v_cvt_pk_bf16_f32 v52, v52, v53
	v_cvt_pk_bf16_f32 v54, v54, v55
	v_cvt_pk_bf16_f32 v56, v56, v57
	v_cvt_pk_bf16_f32 v58, v58, v59
	v_cvt_pk_bf16_f32 v60, v60, v61
	v_cvt_pk_bf16_f32 v62, v62, v63
	v_cvt_pk_bf16_f32 v64, v64, v65
	v_cvt_pk_bf16_f32 v66, v66, v67
	v_cndmask_b32_e64 v37, v38, v36, s[80:81]
	v_cndmask_b32_e64 v39, v36, v38, s[80:81]
	v_cndmask_b32_e64 v41, v42, v40, s[80:81]
	v_cndmask_b32_e64 v43, v40, v42, s[80:81]
	v_cndmask_b32_e64 v45, v46, v44, s[80:81]
	v_cndmask_b32_e64 v47, v44, v46, s[80:81]
	v_cndmask_b32_e64 v49, v50, v48, s[80:81]
	v_cndmask_b32_e64 v51, v48, v50, s[80:81]
	v_cndmask_b32_e64 v53, v54, v52, s[80:81]
	v_cndmask_b32_e64 v55, v52, v54, s[80:81]
	v_cndmask_b32_e64 v57, v58, v56, s[80:81]
	v_cndmask_b32_e64 v59, v56, v58, s[80:81]
	v_cndmask_b32_e64 v61, v62, v60, s[80:81]
	v_cndmask_b32_e64 v63, v60, v62, s[80:81]
	v_cndmask_b32_e64 v65, v66, v64, s[80:81]
	v_cndmask_b32_e64 v67, v64, v66, s[80:81]
	v_mov_b32_dpp v36, v37 row_ror:8 row_mask:0xf bank_mask:0xf
	v_mov_b32_dpp v40, v41 row_ror:8 row_mask:0xf bank_mask:0xf
	v_mov_b32_dpp v44, v45 row_ror:8 row_mask:0xf bank_mask:0xf
	v_mov_b32_dpp v48, v49 row_ror:8 row_mask:0xf bank_mask:0xf
	v_mov_b32_dpp v52, v53 row_ror:8 row_mask:0xf bank_mask:0xf
	v_mov_b32_dpp v56, v57 row_ror:8 row_mask:0xf bank_mask:0xf
	v_mov_b32_dpp v60, v61 row_ror:8 row_mask:0xf bank_mask:0xf
	v_mov_b32_dpp v64, v65 row_ror:8 row_mask:0xf bank_mask:0xf
	s_nop 1
	v_perm_b32 v68, v39, v36, v104
	v_perm_b32 v69, v39, v36, v105
	v_perm_b32 v70, v43, v40, v104
	v_perm_b32 v71, v43, v40, v105
	v_perm_b32 v72, v47, v44, v104
	v_perm_b32 v73, v47, v44, v105
	v_perm_b32 v74, v51, v48, v104
	v_perm_b32 v75, v51, v48, v105
	v_perm_b32 v76, v55, v52, v104
	v_perm_b32 v77, v55, v52, v105
	v_perm_b32 v78, v59, v56, v104
	v_perm_b32 v79, v59, v56, v105
	v_perm_b32 v80, v63, v60, v104
	v_perm_b32 v81, v63, v60, v105
	v_perm_b32 v82, v67, v64, v104
	v_perm_b32 v83, v67, v64, v105
	s_mov_b64 s[76:77], s[34:35]
	s_mov_b32 s79, 0
	s_cmp_ge_u32 s57, s32
	s_cbranch_scc1 .Ldt3_nlB
	s_cmpk_ge_u32 s57, 0x1410
	s_cbranch_scc1 .Ldt3_out3
	s_sub_i32 s0, s57, 0xa08
	s_mul_i32 s2, s0, 0xcc3
	s_lshr_b32 s2, s2, 20
	s_mul_i32 s3, s2, 0x141
	s_sub_u32 s3, s0, s3
	s_lshl_b32 s17, s3, 7
	s_mul_i32 s20, s2, 0x1410000
	s_add_u32 s17, s17, s20
	s_add_u32 s74, s60, s17
	s_addc_u32 s75, s61, 0
	s_mov_b32 s25, 0xa080
	s_lshl_b32 s20, s2, 10
	s_cmpk_lt_u32 s3, 0x80
	s_cbranch_scc1 .Ldt3_wlo3
	s_cmpk_eq_u32 s3, 0x80
	s_cbranch_scc1 .Ldt3_wlr3
	s_add_i32 s3, s3, -1

.Ldt3_nlB:
	ds_write_b32 v84, v68 offset:33280
	ds_write_b32 v84, v69 offset:34320
	ds_write_b32 v84, v70 offset:33408
	ds_write_b32 v84, v71 offset:34448
	ds_write_b32 v84, v72 offset:33536
	ds_write_b32 v84, v73 offset:34576
	ds_write_b32 v84, v74 offset:33664
	ds_write_b32 v84, v75 offset:34704
	ds_write_b32 v84, v76 offset:33792
	ds_write_b32 v84, v77 offset:34832
	ds_write_b32 v84, v78 offset:33920
	ds_write_b32 v84, v79 offset:34960
	ds_write_b32 v84, v80 offset:34048
	ds_write_b32 v84, v81 offset:35088
	ds_write_b32 v84, v82 offset:34176
	ds_write_b32 v84, v83 offset:35216
	s_waitcnt lgkmcnt(0)
	s_barrier
	ds_read_b128 v[68:71], v85 offset:33280
	ds_read_b128 v[72:75], v86 offset:33280
	ds_read_b128 v[76:79], v87 offset:33280
	ds_read_b128 v[80:83], v88 offset:33280
	s_waitcnt lgkmcnt(3)
	global_store_dwordx4 v89, v[68:71], s[76:77]
	s_waitcnt lgkmcnt(2)
	global_store_dwordx4 v90, v[72:75], s[76:77]
	s_waitcnt lgkmcnt(1)
	global_store_dwordx4 v91, v[76:79], s[76:77]
	s_waitcnt lgkmcnt(0)
	global_store_dwordx4 v92, v[80:83], s[76:77]
	s_add_u32 s58, s58, 1
	s_cmp_eq_u32 s78, 0
	s_cbranch_scc0 .Ldt3_procA
.Ldt3_end:
	s_nop 1
	s_waitcnt lgkmcnt(0)
	s_barrier
.Ldt3_skip:
	s_ashr_i32 s0, s56, 31
	s_lshr_b32 s0, s0, 29
	s_add_i32 s17, s56, s0
	s_and_b32 s0, s17, -8
	s_sub_i32 s0, s56, s0
	s_cmp_gt_i32 s0, -1
	s_mov_b64 s[2:3], -1
	s_cbranch_scc0 .LBB0_807
	s_lshl_b32 s16, s0, 6
	s_mov_b64 s[2:3], 0
